# indexer group loop: LDS reads software-pipelined one group ahead
# baseline (speedup 1.0000x reference)
; DI f32x4 mfma16(bf16x8 a, bf16x8 b, f32x4 c) { return __builtin_amdgcn_mfma_f32_16x16x32_bf16(a, b, c, 0, 0, 0); }
; DI float relu_(float x) { return __builtin_amdgcn_fmed3f(x, 0.f, __builtin_inff()); }
; DI void dsa_task(const Params& p, int l, int isP, int b, int tq, char* smem, const bool dry) {
;     ...
;         for (int tg = 0; tg < ngrp; tg++) {
;           unsigned keys[4];
; #pragma unroll
;           for (int tt = 0; tt < 4; tt++) {
;             const bf16_t* br = kst + ((tg * 4 + tt) * 16 + cl) * 72 + g4 * 8;
;             const bf16x8 b0 = *(const bf16x8*)br;
;             const bf16x8 b1 = *(const bf16x8*)(br + 32);
;             f32x4 a = (f32x4){0.f, 0.f, 0.f, 0.f};
;             a = mfma16(aq0, b0, a);
;             a = mfma16(aq1, b1, a);
;             const float score = wq.x * relu_(a[0]) + wq.y * relu_(a[1]) + wq.z * relu_(a[2]) + wq.w * relu_(a[3]);
;             keys[tt] = mono_key(score);
;           }
.Lidx_first:
	ds_read_b128 v[224:227], v123
	ds_read_b128 v[228:231], v123 offset:64
	ds_read_b128 v[232:235], v123 offset:2304
	ds_read_b128 v[236:239], v123 offset:2368
	ds_read_b128 v[240:243], v123 offset:4608
	ds_read_b128 v[244:247], v123 offset:4672
	ds_read_b128 v[248:251], v123 offset:6912
	ds_read_b128 v[124:127], v123 offset:6976
	s_waitcnt lgkmcnt(7)
	v_mfma_f32_16x16x32_bf16 v[60:63], v[4:7], v[224:227], 0
	s_waitcnt lgkmcnt(5)
	v_mfma_f32_16x16x32_bf16 v[56:59], v[4:7], v[232:235], 0
	s_waitcnt lgkmcnt(3)
	v_mfma_f32_16x16x32_bf16 v[52:55], v[4:7], v[240:243], 0
	s_waitcnt lgkmcnt(1)
	v_mfma_f32_16x16x32_bf16 v[48:51], v[4:7], v[248:251], 0
	v_mfma_f32_16x16x32_bf16 v[60:63], v[8:11], v[228:231], v[60:63]
	v_mfma_f32_16x16x32_bf16 v[56:59], v[8:11], v[236:239], v[56:59]
	v_mfma_f32_16x16x32_bf16 v[52:55], v[8:11], v[244:247], v[52:55]
	s_waitcnt lgkmcnt(0)
	v_mfma_f32_16x16x32_bf16 v[48:51], v[8:11], v[124:127], v[48:51]
	s_branch .Lidx_pre

; DI f32x4 mfma16(bf16x8 a, bf16x8 b, f32x4 c) { return __builtin_amdgcn_mfma_f32_16x16x32_bf16(a, b, c, 0, 0, 0); }
; DI float relu_(float x) { return __builtin_amdgcn_fmed3f(x, 0.f, __builtin_inff()); }
; DI void dsa_task(const Params& p, int l, int isP, int b, int tq, char* smem, const bool dry) {
;     ...
;         for (int tg = 0; tg < ngrp; tg++) {
;           unsigned keys[4];
; #pragma unroll
;           for (int tt = 0; tt < 4; tt++) {
;             const bf16_t* br = kst + ((tg * 4 + tt) * 16 + cl) * 72 + g4 * 8;
;             const bf16x8 b0 = *(const bf16x8*)br;
;             const bf16x8 b1 = *(const bf16x8*)(br + 32);
;             f32x4 a = (f32x4){0.f, 0.f, 0.f, 0.f};
;             a = mfma16(aq0, b0, a);
;             a = mfma16(aq1, b1, a);
;             const float score = wq.x * relu_(a[0]) + wq.y * relu_(a[1]) + wq.z * relu_(a[2]) + wq.w * relu_(a[3]);
;             keys[tt] = mono_key(score);
;           }
.LBB0_1311:
	ds_read_b128 v[124:127], v123 offset:6976
	s_cmp_lt_u32 s76, 2
	s_cbranch_scc0 .Lidx_slow
	s_waitcnt lgkmcnt(11)
	v_mfma_f32_16x16x32_bf16 v[60:63], v[4:7], v[224:227], 0
	s_waitcnt lgkmcnt(9)
	v_mfma_f32_16x16x32_bf16 v[56:59], v[4:7], v[232:235], 0
	s_waitcnt lgkmcnt(7)
	v_mfma_f32_16x16x32_bf16 v[52:55], v[4:7], v[240:243], 0
	s_waitcnt lgkmcnt(5)
	v_mfma_f32_16x16x32_bf16 v[48:51], v[4:7], v[248:251], 0
	v_mfma_f32_16x16x32_bf16 v[60:63], v[8:11], v[228:231], v[60:63]
	v_mfma_f32_16x16x32_bf16 v[56:59], v[8:11], v[236:239], v[56:59]
	v_mfma_f32_16x16x32_bf16 v[52:55], v[8:11], v[244:247], v[52:55]
	s_waitcnt lgkmcnt(0)
	v_mfma_f32_16x16x32_bf16 v[48:51], v[8:11], v[124:127], v[48:51]
	s_branch .Lidx_pre
.Lidx_slow:
	s_waitcnt lgkmcnt(0)
	v_mfma_f32_16x16x32_bf16 v[60:63], v[4:7], v[224:227], 0
	v_mfma_f32_16x16x32_bf16 v[56:59], v[4:7], v[232:235], 0
	v_mfma_f32_16x16x32_bf16 v[52:55], v[4:7], v[240:243], 0
	v_mfma_f32_16x16x32_bf16 v[48:51], v[4:7], v[248:251], 0
	v_mfma_f32_16x16x32_bf16 v[60:63], v[8:11], v[228:231], v[60:63]
	v_mfma_f32_16x16x32_bf16 v[56:59], v[8:11], v[236:239], v[56:59]
	v_mfma_f32_16x16x32_bf16 v[52:55], v[8:11], v[244:247], v[52:55]
	v_mfma_f32_16x16x32_bf16 v[48:51], v[8:11], v[124:127], v[48:51]
.Lidx_pre:
	ds_read_b128 v[224:227], v123 offset:9216
	ds_read_b128 v[228:231], v123 offset:9280
	ds_read_b128 v[232:235], v123 offset:11520
	ds_read_b128 v[236:239], v123 offset:11584
	ds_read_b128 v[240:243], v123 offset:13824
	ds_read_b128 v[244:247], v123 offset:13888
	ds_read_b128 v[248:251], v123 offset:16128
	s_cmp_lt_i32 s76, 5
	s_cbranch_scc1 .LBB0_1313
	s_cmp_lg_u32 s76, 5
	s_mov_b64 s[38:39], -1
	s_cselect_b64 s[40:41], -1, 0
	s_cbranch_execz .LBB0_1314
	s_branch .LBB0_1315
